# skip the grid-wide barrier between the independent uq and ukv GEMM phases (workgroup-local drain and s_barrier kept), on top of best
# speedup vs baseline: 1.0024x; 1.0024x over previous
; __device__ __forceinline__ void xcd_barrier(const XcdBarrier& b) {
;     asm volatile("s_waitcnt vmcnt(0)" ::: "memory");
;     __syncthreads();
; __global__ void __launch_bounds__(NTHREADS, 2) fwd_kernel(Args args) {
;     ...
;         if (ph + 1 < args.ph_hi) { if (ph == args.ph_lo) grid.sync(); else xcd_barrier(xbar); }
.LBB0_864:
	v_readlane_b32 s2, v255, 17
	s_add_i32 s16, s2, 1
	s_cmp_ge_i32 s16, s87
	s_mov_b64 s[0:1], -1
	v_readlane_b32 s3, v255, 18
	s_cbranch_scc1 .LBB0_10
	s_cmp_lg_u32 s2, s86
	s_cbranch_scc0 .LBB0_919
	s_waitcnt vmcnt(0)
	s_waitcnt vmcnt(0) lgkmcnt(0)
	s_barrier
	s_cmp_eq_u32 s2, 11
	s_cbranch_scc1 .Lseam_local
	s_cmp_eq_u32 s2, 28
	s_cbranch_scc0 .Lseam_grid

; __device__ __forceinline__ void xcd_barrier(const XcdBarrier& b) {
;     ...
;     if (threadIdx.x == 0) {
;         unsigned* bar = b.bar;
;         __builtin_amdgcn_s_waitcnt(0);
;         unsigned nloc = b.st[0], nx = b.st[1];
;         if (nloc == 0u) { xcd_barrier_complete(bar, b.x, nloc, nx); b.st[0] = nloc; b.st[1] = nx; }
.Lseam_grid:
	s_mov_b64 s[0:1], exec
	v_readlane_b32 s2, v253, 2
	v_readlane_b32 s3, v253, 3
	s_and_b64 s[2:3], s[0:1], s[2:3]
	s_mov_b64 exec, s[2:3]
	s_cbranch_execz .LBB0_918
	v_readlane_b32 s2, v254, 53
	s_waitcnt vmcnt(0) expcnt(0) lgkmcnt(0)
	s_nop 0
	v_mov_b32_e32 v0, s2
	ds_read_b32 v2, v0
	v_readlane_b32 s2, v254, 54
	s_waitcnt lgkmcnt(0)
	v_cmp_ne_u32_e32 vcc, 0, v2
	v_mov_b32_e32 v0, s2
	ds_read_b32 v0, v0
	s_cbranch_vccnz .LBB0_882
	s_mov_b32 s8, 1
	s_branch .LBB0_870
